# as v53 + in-proj tile prologue: full vmcnt(0) drain before the K-loop removed (the loop's own in-order counted waits cover the pending row-norm loads and epilogue stores)
# speedup vs baseline: 1.0071x; 1.0071x over previous
; template <class Epi>
; __device__ __forceinline__ void gemm_phase(LAS unsigned char* lds, const Gemm g, const StaticOrder& S, const Epi& E) {
;     ...
;     for (;;) {
;         const bool has_next = S.next(ui + 1, nxt);
;         const char* nA = has_next ? (const char*)g.A + (size_t)nxt.pm * tstepA + (size_t)(nxt.pn >> 2) * gstepA : cA; const char* nB = has_next ? (const char*)g.Bt + (size_t)nxt.pn * tstepB : cB;
;         for (int t = 0; t < nt; t += 2) {
;             const bool last = (t == nt - 2);
;             const char* a1 = cA + (size_t)(t + 1) * kstepA;
;             const char* a2 = last ? nA : cA + (size_t)(t + 2) * kstepA; const char* b2 = last ? nB : cB + (size_t)(t + 2) * kstep;
;     ...
; #pragma unroll
;         for (int a = 0; a < 2; ++a)
; #pragma unroll
;             for (int b = 0; b < 2; ++b)
; #pragma unroll
;                 for (int m = 0; m < 4; ++m)
; #pragma unroll
;                     for (int n = 0; n < 2; ++n) acc[a][b][m][n] = (f32x4){0.f, 0.f, 0.f, 0.f};
;         cur = nxt; cA = nA; cB = nB; ++ui;
.LBB0_157:
	s_ashr_i32 s23, s22, 31
	s_lshl_b64 s[24:25], s[22:23], 20
	s_add_u32 s26, s10, s24
	s_addc_u32 s27, s11, s25
	s_and_b64 s[24:25], s[40:41], exec
	s_cselect_b32 s23, s27, s39
	s_cselect_b32 s55, s26, s38
	s_ashr_i32 s21, s20, 31
	s_lshl_b64 s[24:25], s[20:21], 20
	s_add_u32 s36, s35, s24
	s_addc_u32 s37, s44, s25
	s_and_b64 s[24:25], s[40:41], exec
	s_cselect_b32 s21, s37, s5
	s_cselect_b32 s56, s36, s4
	s_add_u32 s57, s4, 0x100
	v_mov_b32_e32 v2, 0
	s_addc_u32 s58, s5, 0
	s_mov_b32 s59, -2
	v_mov_b32_e32 v3, v2
	v_mov_b32_e32 v4, v2
	v_mov_b32_e32 v5, v2
	v_mov_b32_e32 v6, v2
	v_mov_b32_e32 v7, v2
	v_mov_b32_e32 v8, v2
	v_mov_b32_e32 v9, v2
	v_mov_b32_e32 v18, v2
	v_mov_b32_e32 v19, v2
	v_mov_b32_e32 v20, v2
	v_mov_b32_e32 v21, v2
	v_mov_b32_e32 v22, v2
	v_mov_b32_e32 v23, v2
	v_mov_b32_e32 v24, v2
	v_mov_b32_e32 v25, v2
	v_mov_b32_e32 v34, v2
	v_mov_b32_e32 v35, v2
	v_mov_b32_e32 v36, v2
	v_mov_b32_e32 v37, v2
	v_mov_b32_e32 v38, v2
	v_mov_b32_e32 v39, v2
	v_mov_b32_e32 v40, v2
	v_mov_b32_e32 v41, v2
	v_mov_b32_e32 v50, v2
	v_mov_b32_e32 v51, v2
	v_mov_b32_e32 v52, v2
	v_mov_b32_e32 v53, v2
	v_mov_b32_e32 v54, v2
	v_mov_b32_e32 v55, v2
	v_mov_b32_e32 v56, v2
	v_mov_b32_e32 v57, v2
	v_mov_b32_e32 v10, v2
	v_mov_b32_e32 v11, v2
	v_mov_b32_e32 v12, v2
	v_mov_b32_e32 v13, v2
	v_mov_b32_e32 v14, v2
	v_mov_b32_e32 v15, v2
	v_mov_b32_e32 v16, v2
	v_mov_b32_e32 v17, v2
	v_mov_b32_e32 v26, v2
	v_mov_b32_e32 v27, v2
	v_mov_b32_e32 v28, v2
	v_mov_b32_e32 v29, v2
	v_mov_b32_e32 v30, v2
	v_mov_b32_e32 v31, v2
	v_mov_b32_e32 v32, v2
	v_mov_b32_e32 v33, v2
	v_mov_b32_e32 v42, v2
	v_mov_b32_e32 v43, v2
	v_mov_b32_e32 v44, v2
	v_mov_b32_e32 v45, v2
	v_mov_b32_e32 v46, v2
	v_mov_b32_e32 v47, v2
	v_mov_b32_e32 v48, v2
	v_mov_b32_e32 v49, v2
	v_mov_b32_e32 v58, v2
	v_mov_b32_e32 v59, v2
	v_mov_b32_e32 v60, v2
	v_mov_b32_e32 v61, v2
	v_mov_b32_e32 v62, v2
	v_mov_b32_e32 v63, v2
	v_mov_b32_e32 v64, v2
	v_mov_b32_e32 v65, v2
	v_mov_b32_e32 v66, v2
	v_mov_b32_e32 v67, v2
	v_mov_b32_e32 v68, v2
	v_mov_b32_e32 v69, v2
	v_mov_b32_e32 v70, v2
	v_mov_b32_e32 v71, v2
	v_mov_b32_e32 v72, v2
	v_mov_b32_e32 v73, v2
	v_mov_b32_e32 v82, v2
	v_mov_b32_e32 v83, v2
	v_mov_b32_e32 v84, v2
	v_mov_b32_e32 v85, v2
	v_mov_b32_e32 v86, v2
	v_mov_b32_e32 v87, v2
	v_mov_b32_e32 v88, v2
	v_mov_b32_e32 v89, v2
	v_mov_b32_e32 v98, v2
	v_mov_b32_e32 v99, v2
	v_mov_b32_e32 v100, v2
	v_mov_b32_e32 v101, v2
	v_mov_b32_e32 v102, v2
	v_mov_b32_e32 v103, v2
	v_mov_b32_e32 v104, v2
	v_mov_b32_e32 v105, v2
	v_mov_b32_e32 v114, v2
	v_mov_b32_e32 v115, v2
	v_mov_b32_e32 v116, v2
	v_mov_b32_e32 v117, v2
	v_mov_b32_e32 v118, v2
	v_mov_b32_e32 v119, v2
	v_mov_b32_e32 v120, v2
	v_mov_b32_e32 v121, v2
	v_mov_b32_e32 v74, v2
	v_mov_b32_e32 v75, v2
	v_mov_b32_e32 v76, v2
	v_mov_b32_e32 v77, v2
	v_mov_b32_e32 v78, v2
	v_mov_b32_e32 v79, v2
	v_mov_b32_e32 v80, v2
	v_mov_b32_e32 v81, v2
	v_mov_b32_e32 v90, v2
	v_mov_b32_e32 v91, v2
	v_mov_b32_e32 v92, v2
	v_mov_b32_e32 v93, v2
	v_mov_b32_e32 v94, v2
	v_mov_b32_e32 v95, v2
	v_mov_b32_e32 v96, v2
	v_mov_b32_e32 v97, v2
	v_mov_b32_e32 v106, v2
	v_mov_b32_e32 v107, v2
	v_mov_b32_e32 v108, v2
	v_mov_b32_e32 v109, v2
	v_mov_b32_e32 v110, v2
	v_mov_b32_e32 v111, v2
	v_mov_b32_e32 v112, v2
	v_mov_b32_e32 v113, v2
	v_mov_b32_e32 v122, v2
	v_mov_b32_e32 v123, v2
	v_mov_b32_e32 v124, v2
	v_mov_b32_e32 v125, v2
	v_mov_b32_e32 v126, v2
	v_mov_b32_e32 v127, v2
	v_mov_b32_e32 v128, v2
	v_mov_b32_e32 v129, v2
	v_add_u32_e32 v250, 0x10000, v152
